# accumulators cleared two registers at a time with v_pk_mov_b32 (63 instead of 126 moves per unit)
# baseline (speedup 1.0000x reference)
;     __host__ __device__ bool next(int i, Unit& u) const { return i < cnt ? so.next(base + i, u) : false; }
;     __host__ __device__ bool next(int i, Unit& u) const { const int L = i * G + c; if (L >= 32) return false; u.g = L >> 3; u.pm = L & 7; u.pn = 0; return true; }
; #define PG8_WAIT_V(n) asm volatile("s_waitcnt vmcnt(" #n ")" ::: "memory")
; #define PG8_BAR __builtin_amdgcn_s_barrier()
; template <class Epi, class Sched, bool ALIGN_EPI = false, bool SP2 = false>
; __device__ __forceinline__ void gemm_phase(PG8_LAS unsigned char* lds, const Gemm g, const Sched& S, const Epi& E) {
;     ...
; #pragma unroll
;     for (int a = 0; a < 2; ++a)
; #pragma unroll
;         for (int b = 0; b < 2; ++b)
; #pragma unroll
;             for (int m = 0; m < 4; ++m)
; #pragma unroll
;                 for (int n = 0; n < 2; ++n) acc[a][b][m][n] = (f32x4){0.f, 0.f, 0.f, 0.f};
;     bf16x8 At[4][2], B0[2][2], B1[2][2];
;     const char* cA = (const char*)(g.A + (size_t)cur.g * g.gsA) + (size_t)cur.pm * tstepA; const char* cB = (const char*)(g.Bt + (size_t)cur.g * g.gsB) + (size_t)cur.pn * tstepB;
;     S.a_ready(cur);
;     if constexpr (SP2) {
;         PG8_STAGE(PG8_SB(0, 0), cB, voffB); PG8_STAGE(PG8_SB(0, 1), cB + hstepB, voffB); PG8_STAGE(PG8_SA(0, 0), cA, voffA); PG8_STAGE(PG8_SA(0, 1), cA + hstepA, voffA);
;         if (wr == 1) PG8_BAR;
;         PG8_WAIT_V(2); PG8_BAR;
;         PG8_STAGE(PG8_SB(1, 0), cB + kstep, voffB); PG8_STAGE(PG8_SA(1, 0), cA + kstep, voffA); PG8_STAGE(PG8_SB(1, 1), cB + hstepB + kstep, voffB);
;         PG8_WAIT_V(6); PG8_BAR;
;     } else {
;         PG8_STAGE(PG8_SB(0, 0), cB, voffB); PG8_STAGE(PG8_SA(0, 0), cA, voffA); PG8_STAGE(PG8_SB(0, 1), cB + hstepB, voffB); PG8_STAGE(PG8_SA(0, 1), cA + hstepA, voffA);
;         if (wr == 1) PG8_BAR;
;         PG8_WAIT_V(4); PG8_BAR;
;         PG8_STAGE(PG8_SB(1, 0), cB + kstep, voffB); PG8_STAGE(PG8_SA(1, 0), cA + kstep, voffA); PG8_STAGE(PG8_SB(1, 1), cB + hstepB + kstep, voffB);
;         PG8_WAIT_V(6); PG8_BAR;
;     }
;     for (;;) {
;         const bool has_next = S.next(ui + 1, nxt);
;         const char* nA = has_next ? (const char*)(g.A + (size_t)nxt.g * g.gsA) + (size_t)nxt.pm * tstepA : cA; const char* nB = has_next ? (const char*)(g.Bt + (size_t)nxt.g * g.gsB) + (size_t)nxt.pn * tstepB : cB;
.LBB0_84:
	s_ashr_i32 s25, s24, 31
	s_lshl_b64 s[26:27], s[24:25], 20
	s_add_u32 s26, s37, s26
	s_addc_u32 s27, s38, s27
	s_ashr_i32 s23, s22, 31
	s_lshl_b64 s[28:29], s[22:23], 20
	s_add_u32 s28, s39, s28
	v_mov_b32_e32 v127, 0
	s_addc_u32 s29, s44, s29
	s_and_b64 vcc, exec, s[6:7]
	v_mov_b32_e32 v126, v127
	v_pk_mov_b32 v[124:125], v[126:127], v[126:127]
	v_pk_mov_b32 v[122:123], v[126:127], v[126:127]
	v_pk_mov_b32 v[120:121], v[126:127], v[126:127]
	v_pk_mov_b32 v[110:111], v[126:127], v[126:127]
	v_pk_mov_b32 v[108:109], v[126:127], v[126:127]
	v_pk_mov_b32 v[106:107], v[126:127], v[126:127]
	v_pk_mov_b32 v[104:105], v[126:127], v[126:127]
	v_pk_mov_b32 v[94:95], v[126:127], v[126:127]
	v_pk_mov_b32 v[92:93], v[126:127], v[126:127]
	v_pk_mov_b32 v[90:91], v[126:127], v[126:127]
	v_pk_mov_b32 v[88:89], v[126:127], v[126:127]
	v_pk_mov_b32 v[78:79], v[126:127], v[126:127]
	v_pk_mov_b32 v[76:77], v[126:127], v[126:127]
	v_pk_mov_b32 v[74:75], v[126:127], v[126:127]
	v_pk_mov_b32 v[72:73], v[126:127], v[126:127]
	v_pk_mov_b32 v[118:119], v[126:127], v[126:127]
	v_pk_mov_b32 v[116:117], v[126:127], v[126:127]
	v_pk_mov_b32 v[114:115], v[126:127], v[126:127]
	v_pk_mov_b32 v[112:113], v[126:127], v[126:127]
	v_pk_mov_b32 v[102:103], v[126:127], v[126:127]
	v_pk_mov_b32 v[100:101], v[126:127], v[126:127]
	v_pk_mov_b32 v[98:99], v[126:127], v[126:127]
	v_pk_mov_b32 v[96:97], v[126:127], v[126:127]
	v_pk_mov_b32 v[86:87], v[126:127], v[126:127]
	v_pk_mov_b32 v[84:85], v[126:127], v[126:127]
	v_pk_mov_b32 v[82:83], v[126:127], v[126:127]
	v_pk_mov_b32 v[80:81], v[126:127], v[126:127]
	v_pk_mov_b32 v[70:71], v[126:127], v[126:127]
	v_pk_mov_b32 v[68:69], v[126:127], v[126:127]
	v_pk_mov_b32 v[66:67], v[126:127], v[126:127]
	v_pk_mov_b32 v[64:65], v[126:127], v[126:127]
	v_pk_mov_b32 v[62:63], v[126:127], v[126:127]
	v_pk_mov_b32 v[60:61], v[126:127], v[126:127]
	v_pk_mov_b32 v[58:59], v[126:127], v[126:127]
	v_pk_mov_b32 v[56:57], v[126:127], v[126:127]
	v_pk_mov_b32 v[46:47], v[126:127], v[126:127]
	v_pk_mov_b32 v[44:45], v[126:127], v[126:127]
	v_pk_mov_b32 v[42:43], v[126:127], v[126:127]
	v_pk_mov_b32 v[40:41], v[126:127], v[126:127]
	v_pk_mov_b32 v[30:31], v[126:127], v[126:127]
	v_pk_mov_b32 v[28:29], v[126:127], v[126:127]
	v_pk_mov_b32 v[26:27], v[126:127], v[126:127]
	v_pk_mov_b32 v[24:25], v[126:127], v[126:127]
	v_pk_mov_b32 v[14:15], v[126:127], v[126:127]
	v_pk_mov_b32 v[12:13], v[126:127], v[126:127]
	v_pk_mov_b32 v[10:11], v[126:127], v[126:127]
	v_pk_mov_b32 v[8:9], v[126:127], v[126:127]
	v_pk_mov_b32 v[54:55], v[126:127], v[126:127]
	v_pk_mov_b32 v[52:53], v[126:127], v[126:127]
	v_pk_mov_b32 v[50:51], v[126:127], v[126:127]
	v_pk_mov_b32 v[48:49], v[126:127], v[126:127]
	v_pk_mov_b32 v[38:39], v[126:127], v[126:127]
	v_pk_mov_b32 v[36:37], v[126:127], v[126:127]
	v_pk_mov_b32 v[34:35], v[126:127], v[126:127]
	v_pk_mov_b32 v[32:33], v[126:127], v[126:127]
	v_pk_mov_b32 v[22:23], v[126:127], v[126:127]
	v_pk_mov_b32 v[20:21], v[126:127], v[126:127]
	v_pk_mov_b32 v[18:19], v[126:127], v[126:127]
	v_pk_mov_b32 v[16:17], v[126:127], v[126:127]
	v_pk_mov_b32 v[6:7], v[126:127], v[126:127]
	v_pk_mov_b32 v[4:5], v[126:127], v[126:127]
	v_pk_mov_b32 v[2:3], v[126:127], v[126:127]
	s_waitcnt lgkmcnt(0)
	v_pk_mov_b32 v[0:1], v[126:127], v[126:127]
	s_cbranch_vccnz .LBB0_87
	s_and_b64 s[34:35], s[8:9], exec
	s_cselect_b32 s11, s27, s31
	s_cselect_b32 s23, s26, s30
	s_cselect_b32 s25, s29, s13
	s_cselect_b32 s40, s28, s12
	s_add_u32 s41, s12, 0x100
	s_addc_u32 s42, s13, 0
	s_add_u32 s12, s30, 0x80080
	s_addc_u32 s13, s31, 0
	s_mov_b32 s30, 0

;     __host__ __device__ bool next(int i, Unit& u) const { return i < cnt ? so.next(base + i, u) : false; }
;     __host__ __device__ bool next(int i, Unit& u) const { const int L = i * G + c; if (L >= 32) return false; u.g = L >> 3; u.pm = L & 7; u.pn = 0; return true; }
; #define PG8_WAIT_V(n) asm volatile("s_waitcnt vmcnt(" #n ")" ::: "memory")
; #define PG8_BAR __builtin_amdgcn_s_barrier()
; template <class Epi, class Sched, bool ALIGN_EPI = false, bool SP2 = false>
; __device__ __forceinline__ void gemm_phase(PG8_LAS unsigned char* lds, const Gemm g, const Sched& S, const Epi& E) {
;     ...
; #pragma unroll
;     for (int a = 0; a < 2; ++a)
; #pragma unroll
;         for (int b = 0; b < 2; ++b)
; #pragma unroll
;             for (int m = 0; m < 4; ++m)
; #pragma unroll
;                 for (int n = 0; n < 2; ++n) acc[a][b][m][n] = (f32x4){0.f, 0.f, 0.f, 0.f};
;     bf16x8 At[4][2], B0[2][2], B1[2][2];
;     const char* cA = (const char*)(g.A + (size_t)cur.g * g.gsA) + (size_t)cur.pm * tstepA; const char* cB = (const char*)(g.Bt + (size_t)cur.g * g.gsB) + (size_t)cur.pn * tstepB;
;     S.a_ready(cur);
;     if constexpr (SP2) {
;         PG8_STAGE(PG8_SB(0, 0), cB, voffB); PG8_STAGE(PG8_SB(0, 1), cB + hstepB, voffB); PG8_STAGE(PG8_SA(0, 0), cA, voffA); PG8_STAGE(PG8_SA(0, 1), cA + hstepA, voffA);
;         if (wr == 1) PG8_BAR;
;         PG8_WAIT_V(2); PG8_BAR;
;         PG8_STAGE(PG8_SB(1, 0), cB + kstep, voffB); PG8_STAGE(PG8_SA(1, 0), cA + kstep, voffA); PG8_STAGE(PG8_SB(1, 1), cB + hstepB + kstep, voffB);
;         PG8_WAIT_V(6); PG8_BAR;
;     } else {
;         PG8_STAGE(PG8_SB(0, 0), cB, voffB); PG8_STAGE(PG8_SA(0, 0), cA, voffA); PG8_STAGE(PG8_SB(0, 1), cB + hstepB, voffB); PG8_STAGE(PG8_SA(0, 1), cA + hstepA, voffA);
;         if (wr == 1) PG8_BAR;
;         PG8_WAIT_V(4); PG8_BAR;
;         PG8_STAGE(PG8_SB(1, 0), cB + kstep, voffB); PG8_STAGE(PG8_SA(1, 0), cA + kstep, voffA); PG8_STAGE(PG8_SB(1, 1), cB + hstepB + kstep, voffB);
;         PG8_WAIT_V(6); PG8_BAR;
;     }
;     for (;;) {
;         const bool has_next = S.next(ui + 1, nxt);
;         const char* nA = has_next ? (const char*)(g.A + (size_t)nxt.g * g.gsA) + (size_t)nxt.pm * tstepA : cA; const char* nB = has_next ? (const char*)(g.Bt + (size_t)nxt.g * g.gsB) + (size_t)nxt.pn * tstepB : cB;
.LBB0_252:
	s_add_i32 s55, s55, 1
	s_mul_i32 s28, s55, s33
	s_add_i32 s28, s28, s2
	s_mov_b32 s19, s64
	s_mov_b32 s30, s63
	s_and_b32 s64, s28, 7
	s_ashr_i32 s63, s28, 3
	s_cmp_lt_i32 s28, 32
	s_cselect_b64 s[34:35], -1, 0
	s_and_b64 s[28:29], s[34:35], exec
	s_cselect_b32 s30, s63, s30
	s_cselect_b32 s28, s64, s19
	s_ashr_i32 s31, s30, 31
	s_lshl_b64 s[44:45], s[30:31], 9
	s_add_u32 s19, s37, s44
	s_addc_u32 s44, s38, s45
	s_ashr_i32 s29, s28, 31
	s_lshl_b64 s[28:29], s[28:29], 19
	s_add_u32 s28, s19, s28
	s_addc_u32 s29, s44, s29
	s_lshl_b64 s[30:31], s[30:31], 17
	s_add_u32 s30, s39, s30
	v_mov_b32_e32 v127, 0
	s_addc_u32 s31, s46, s31
	s_and_b64 vcc, exec, s[4:5]
	v_mov_b32_e32 v126, v127
	v_pk_mov_b32 v[124:125], v[126:127], v[126:127]
	v_pk_mov_b32 v[122:123], v[126:127], v[126:127]
	v_pk_mov_b32 v[120:121], v[126:127], v[126:127]
	v_pk_mov_b32 v[110:111], v[126:127], v[126:127]
	v_pk_mov_b32 v[108:109], v[126:127], v[126:127]
	v_pk_mov_b32 v[106:107], v[126:127], v[126:127]
	v_pk_mov_b32 v[104:105], v[126:127], v[126:127]
	v_pk_mov_b32 v[94:95], v[126:127], v[126:127]
	v_pk_mov_b32 v[92:93], v[126:127], v[126:127]
	v_pk_mov_b32 v[90:91], v[126:127], v[126:127]
	v_pk_mov_b32 v[88:89], v[126:127], v[126:127]
	v_pk_mov_b32 v[78:79], v[126:127], v[126:127]
	v_pk_mov_b32 v[76:77], v[126:127], v[126:127]
	v_pk_mov_b32 v[74:75], v[126:127], v[126:127]
	v_pk_mov_b32 v[72:73], v[126:127], v[126:127]
	v_pk_mov_b32 v[118:119], v[126:127], v[126:127]
	v_pk_mov_b32 v[116:117], v[126:127], v[126:127]
	v_pk_mov_b32 v[114:115], v[126:127], v[126:127]
	v_pk_mov_b32 v[112:113], v[126:127], v[126:127]
	v_pk_mov_b32 v[102:103], v[126:127], v[126:127]
	v_pk_mov_b32 v[100:101], v[126:127], v[126:127]
	v_pk_mov_b32 v[98:99], v[126:127], v[126:127]
	v_pk_mov_b32 v[96:97], v[126:127], v[126:127]
	v_pk_mov_b32 v[86:87], v[126:127], v[126:127]
	v_pk_mov_b32 v[84:85], v[126:127], v[126:127]
	v_pk_mov_b32 v[82:83], v[126:127], v[126:127]
	v_pk_mov_b32 v[80:81], v[126:127], v[126:127]
	v_pk_mov_b32 v[70:71], v[126:127], v[126:127]
	v_pk_mov_b32 v[68:69], v[126:127], v[126:127]
	v_pk_mov_b32 v[66:67], v[126:127], v[126:127]
	v_pk_mov_b32 v[64:65], v[126:127], v[126:127]
	v_pk_mov_b32 v[62:63], v[126:127], v[126:127]
	v_pk_mov_b32 v[60:61], v[126:127], v[126:127]
	v_pk_mov_b32 v[58:59], v[126:127], v[126:127]
	v_pk_mov_b32 v[56:57], v[126:127], v[126:127]
	v_pk_mov_b32 v[46:47], v[126:127], v[126:127]
	v_pk_mov_b32 v[44:45], v[126:127], v[126:127]
	v_pk_mov_b32 v[42:43], v[126:127], v[126:127]
	v_pk_mov_b32 v[40:41], v[126:127], v[126:127]
	v_pk_mov_b32 v[30:31], v[126:127], v[126:127]
	v_pk_mov_b32 v[28:29], v[126:127], v[126:127]
	v_pk_mov_b32 v[26:27], v[126:127], v[126:127]
	v_pk_mov_b32 v[24:25], v[126:127], v[126:127]
	v_pk_mov_b32 v[14:15], v[126:127], v[126:127]
	v_pk_mov_b32 v[12:13], v[126:127], v[126:127]
	v_pk_mov_b32 v[10:11], v[126:127], v[126:127]
	v_pk_mov_b32 v[8:9], v[126:127], v[126:127]
	v_pk_mov_b32 v[54:55], v[126:127], v[126:127]
	v_pk_mov_b32 v[52:53], v[126:127], v[126:127]
	v_pk_mov_b32 v[50:51], v[126:127], v[126:127]
	v_pk_mov_b32 v[48:49], v[126:127], v[126:127]
	v_pk_mov_b32 v[38:39], v[126:127], v[126:127]
	v_pk_mov_b32 v[36:37], v[126:127], v[126:127]
	v_pk_mov_b32 v[34:35], v[126:127], v[126:127]
	v_pk_mov_b32 v[32:33], v[126:127], v[126:127]
	v_pk_mov_b32 v[22:23], v[126:127], v[126:127]
	v_pk_mov_b32 v[20:21], v[126:127], v[126:127]
	v_pk_mov_b32 v[18:19], v[126:127], v[126:127]
	v_pk_mov_b32 v[16:17], v[126:127], v[126:127]
	v_pk_mov_b32 v[6:7], v[126:127], v[126:127]
	v_pk_mov_b32 v[4:5], v[126:127], v[126:127]
	v_pk_mov_b32 v[2:3], v[126:127], v[126:127]
	v_pk_mov_b32 v[0:1], v[126:127], v[126:127]
	s_cbranch_vccnz .LBB0_255
	s_and_b64 s[44:45], s[34:35], exec
	s_cselect_b32 s19, s29, s43
	s_cselect_b32 s65, s28, s42
	s_cselect_b32 s66, s31, s41
	s_cselect_b32 s67, s30, s40
	s_add_u32 s68, s40, 0x100
	s_addc_u32 s69, s41, 0
	s_add_u32 s40, s42, 0x40080
	s_addc_u32 s41, s43, 0
	s_mov_b32 s42, 0

;     __host__ __device__ bool next(int i, Unit& u) const { return i < cnt ? so.next(base + i, u) : false; }
;     __host__ __device__ bool next(int i, Unit& u) const { const int L = i * G + c; if (L >= 32) return false; u.g = L >> 3; u.pm = L & 7; u.pn = 0; return true; }
; #define PG8_WAIT_V(n) asm volatile("s_waitcnt vmcnt(" #n ")" ::: "memory")
; #define PG8_BAR __builtin_amdgcn_s_barrier()
; template <class Epi, class Sched, bool ALIGN_EPI = false, bool SP2 = false>
; __device__ __forceinline__ void gemm_phase(PG8_LAS unsigned char* lds, const Gemm g, const Sched& S, const Epi& E) {
;     ...
; #pragma unroll
;     for (int a = 0; a < 2; ++a)
; #pragma unroll
;         for (int b = 0; b < 2; ++b)
; #pragma unroll
;             for (int m = 0; m < 4; ++m)
; #pragma unroll
;                 for (int n = 0; n < 2; ++n) acc[a][b][m][n] = (f32x4){0.f, 0.f, 0.f, 0.f};
;     bf16x8 At[4][2], B0[2][2], B1[2][2];
;     const char* cA = (const char*)(g.A + (size_t)cur.g * g.gsA) + (size_t)cur.pm * tstepA; const char* cB = (const char*)(g.Bt + (size_t)cur.g * g.gsB) + (size_t)cur.pn * tstepB;
;     S.a_ready(cur);
;     if constexpr (SP2) {
;         PG8_STAGE(PG8_SB(0, 0), cB, voffB); PG8_STAGE(PG8_SB(0, 1), cB + hstepB, voffB); PG8_STAGE(PG8_SA(0, 0), cA, voffA); PG8_STAGE(PG8_SA(0, 1), cA + hstepA, voffA);
;         if (wr == 1) PG8_BAR;
;         PG8_WAIT_V(2); PG8_BAR;
;         PG8_STAGE(PG8_SB(1, 0), cB + kstep, voffB); PG8_STAGE(PG8_SA(1, 0), cA + kstep, voffA); PG8_STAGE(PG8_SB(1, 1), cB + hstepB + kstep, voffB);
;         PG8_WAIT_V(6); PG8_BAR;
;     } else {
;         PG8_STAGE(PG8_SB(0, 0), cB, voffB); PG8_STAGE(PG8_SA(0, 0), cA, voffA); PG8_STAGE(PG8_SB(0, 1), cB + hstepB, voffB); PG8_STAGE(PG8_SA(0, 1), cA + hstepA, voffA);
;         if (wr == 1) PG8_BAR;
;         PG8_WAIT_V(4); PG8_BAR;
;         PG8_STAGE(PG8_SB(1, 0), cB + kstep, voffB); PG8_STAGE(PG8_SA(1, 0), cA + kstep, voffA); PG8_STAGE(PG8_SB(1, 1), cB + hstepB + kstep, voffB);
;         PG8_WAIT_V(6); PG8_BAR;
;     }
;     for (;;) {
;         const bool has_next = S.next(ui + 1, nxt);
;         const char* nA = has_next ? (const char*)(g.A + (size_t)nxt.g * g.gsA) + (size_t)nxt.pm * tstepA : cA; const char* nB = has_next ? (const char*)(g.Bt + (size_t)nxt.g * g.gsB) + (size_t)nxt.pn * tstepB : cB;
.LBB0_742:
	s_ashr_i32 s31, s30, 31
	s_lshl_b64 s[34:35], s[30:31], 20
	s_add_u32 s34, s39, s34
	s_addc_u32 s35, s48, s35
	s_ashr_i32 s29, s28, 31
	s_lshl_b64 s[36:37], s[28:29], 20
	s_add_u32 s36, s49, s36
	v_mov_b32_e32 v123, 0
	s_addc_u32 s37, s50, s37
	s_andn2_b64 vcc, exec, s[16:17]
	v_mov_b32_e32 v122, v123
	v_pk_mov_b32 v[120:121], v[122:123], v[122:123]
	v_pk_mov_b32 v[126:127], v[122:123], v[122:123]
	v_pk_mov_b32 v[124:125], v[122:123], v[122:123]
	v_pk_mov_b32 v[110:111], v[122:123], v[122:123]
	v_pk_mov_b32 v[108:109], v[122:123], v[122:123]
	v_pk_mov_b32 v[106:107], v[122:123], v[122:123]
	v_pk_mov_b32 v[104:105], v[122:123], v[122:123]
	v_pk_mov_b32 v[94:95], v[122:123], v[122:123]
	v_pk_mov_b32 v[92:93], v[122:123], v[122:123]
	v_pk_mov_b32 v[90:91], v[122:123], v[122:123]
	v_pk_mov_b32 v[88:89], v[122:123], v[122:123]
	v_pk_mov_b32 v[78:79], v[122:123], v[122:123]
	v_pk_mov_b32 v[76:77], v[122:123], v[122:123]
	v_pk_mov_b32 v[74:75], v[122:123], v[122:123]
	v_pk_mov_b32 v[72:73], v[122:123], v[122:123]
	v_pk_mov_b32 v[118:119], v[122:123], v[122:123]
	v_pk_mov_b32 v[116:117], v[122:123], v[122:123]
	v_pk_mov_b32 v[114:115], v[122:123], v[122:123]
	v_pk_mov_b32 v[112:113], v[122:123], v[122:123]
	v_pk_mov_b32 v[102:103], v[122:123], v[122:123]
	v_pk_mov_b32 v[100:101], v[122:123], v[122:123]
	v_pk_mov_b32 v[98:99], v[122:123], v[122:123]
	v_pk_mov_b32 v[96:97], v[122:123], v[122:123]
	v_pk_mov_b32 v[86:87], v[122:123], v[122:123]
	v_pk_mov_b32 v[84:85], v[122:123], v[122:123]
	v_pk_mov_b32 v[82:83], v[122:123], v[122:123]
	v_pk_mov_b32 v[80:81], v[122:123], v[122:123]
	v_pk_mov_b32 v[70:71], v[122:123], v[122:123]
	v_pk_mov_b32 v[68:69], v[122:123], v[122:123]
	v_pk_mov_b32 v[66:67], v[122:123], v[122:123]
	v_pk_mov_b32 v[64:65], v[122:123], v[122:123]
	v_pk_mov_b32 v[62:63], v[122:123], v[122:123]
	v_pk_mov_b32 v[60:61], v[122:123], v[122:123]
	v_pk_mov_b32 v[58:59], v[122:123], v[122:123]
	v_pk_mov_b32 v[56:57], v[122:123], v[122:123]
	v_pk_mov_b32 v[46:47], v[122:123], v[122:123]
	v_pk_mov_b32 v[44:45], v[122:123], v[122:123]
	v_pk_mov_b32 v[42:43], v[122:123], v[122:123]
	v_pk_mov_b32 v[40:41], v[122:123], v[122:123]
	v_pk_mov_b32 v[30:31], v[122:123], v[122:123]
	v_pk_mov_b32 v[28:29], v[122:123], v[122:123]
	v_pk_mov_b32 v[26:27], v[122:123], v[122:123]
	v_pk_mov_b32 v[24:25], v[122:123], v[122:123]
	v_pk_mov_b32 v[14:15], v[122:123], v[122:123]
	v_pk_mov_b32 v[12:13], v[122:123], v[122:123]
	v_pk_mov_b32 v[10:11], v[122:123], v[122:123]
	v_pk_mov_b32 v[8:9], v[122:123], v[122:123]
	v_pk_mov_b32 v[54:55], v[122:123], v[122:123]
	v_pk_mov_b32 v[52:53], v[122:123], v[122:123]
	v_pk_mov_b32 v[50:51], v[122:123], v[122:123]
	v_pk_mov_b32 v[48:49], v[122:123], v[122:123]
	v_pk_mov_b32 v[38:39], v[122:123], v[122:123]
	v_pk_mov_b32 v[36:37], v[122:123], v[122:123]
	v_pk_mov_b32 v[34:35], v[122:123], v[122:123]
	v_pk_mov_b32 v[32:33], v[122:123], v[122:123]
	v_pk_mov_b32 v[22:23], v[122:123], v[122:123]
	v_pk_mov_b32 v[20:21], v[122:123], v[122:123]
	v_pk_mov_b32 v[18:19], v[122:123], v[122:123]
	v_pk_mov_b32 v[16:17], v[122:123], v[122:123]
	v_pk_mov_b32 v[6:7], v[122:123], v[122:123]
	v_pk_mov_b32 v[4:5], v[122:123], v[122:123]
	s_waitcnt lgkmcnt(0)
	v_pk_mov_b32 v[2:3], v[122:123], v[122:123]
	v_pk_mov_b32 v[0:1], v[122:123], v[122:123]
	s_cbranch_vccnz .LBB0_745
	s_and_b64 s[46:47], s[6:7], exec
	s_cselect_b32 s29, s35, s45
	s_cselect_b32 s31, s34, s44
	s_cselect_b32 s63, s37, s43
	s_cselect_b32 s64, s36, s42
	s_add_u32 s65, s42, 0x100
	s_addc_u32 s66, s43, 0
	s_add_u32 s42, s44, 0x80080
	s_addc_u32 s43, s45, 0
	s_mov_b32 s44, 0

;     __host__ __device__ bool next(int i, Unit& u) const { return i < cnt ? so.next(base + i, u) : false; }
;     __host__ __device__ bool next(int i, Unit& u) const { const int L = i * G + c; if (L >= 32) return false; u.g = L >> 3; u.pm = L & 7; u.pn = 0; return true; }
;   __device__ __forceinline__ bool next(int i,AttnUnit&u)const{ if(i>=4)return false; const int s=vcu&7; u.bh=vcu>>3; u.qb=(i==0)?s:(i==1)?15-s:(i==2)?16+s:31-s; return true; }
; template <class Epi, class Sched, bool ALIGN_EPI = false, bool SP2 = false>
; __device__ __forceinline__ void gemm_phase(PG8_LAS unsigned char* lds, const Gemm g, const Sched& S, const Epi& E) {
;     ...
;         const bool has_next = S.next(ui + 1, nxt);
;         const char* nA = has_next ? (const char*)(g.A + (size_t)nxt.g * g.gsA) + (size_t)nxt.pm * tstepA : cA; const char* nB = has_next ? (const char*)(g.Bt + (size_t)nxt.g * g.gsB) + (size_t)nxt.pn * tstepB : cB;
;         for (int t = 0; t < nt; t += 2) {
;             if constexpr (Epi::MIDK) { if (t == (nt >> 1)) { asm volatile("s_waitcnt vmcnt(0)" ::: "memory"); E.mid(acc, cur, wr, wc, fr, fq); asm volatile("s_waitcnt vmcnt(0)" ::: "memory"); } }
;             const bool last = (t == nt - 2);
;             const char* a1 = cA + (size_t)(t + 1) * kstep;
;             const char* a2 = last ? nA : cA + (size_t)(t + 2) * kstep; const char* b2 = last ? nB : cB + (size_t)(t + 2) * kstep;
;             const char* a3 = a2 + kstep; const char* b3 = b2 + kstep;
;     ...
; #pragma unroll
;         for (int a = 0; a < 2; ++a)
; #pragma unroll
;             for (int b = 0; b < 2; ++b)
; #pragma unroll
;                 for (int m = 0; m < 4; ++m)
; #pragma unroll
;                     for (int n = 0; n < 2; ++n) acc[a][b][m][n] = (f32x4){0.f, 0.f, 0.f, 0.f};
.LBB0_827:
	s_ashr_i32 s35, s34, 31
	s_lshl_b64 s[36:37], s[34:35], 20
	s_add_u32 s36, s47, s36
	s_addc_u32 s37, s48, s37
	s_ashr_i32 s31, s30, 31
	s_lshl_b64 s[38:39], s[30:31], 20
	s_add_u32 s38, s49, s38
	v_mov_b32_e32 v123, 0
	s_addc_u32 s39, s50, s39
	s_andn2_b64 vcc, exec, s[18:19]
	v_mov_b32_e32 v122, v123
	v_pk_mov_b32 v[120:121], v[122:123], v[122:123]
	v_pk_mov_b32 v[126:127], v[122:123], v[122:123]
	v_pk_mov_b32 v[124:125], v[122:123], v[122:123]
	v_pk_mov_b32 v[110:111], v[122:123], v[122:123]
	v_pk_mov_b32 v[108:109], v[122:123], v[122:123]
	v_pk_mov_b32 v[106:107], v[122:123], v[122:123]
	v_pk_mov_b32 v[104:105], v[122:123], v[122:123]
	v_pk_mov_b32 v[94:95], v[122:123], v[122:123]
	v_pk_mov_b32 v[92:93], v[122:123], v[122:123]
	v_pk_mov_b32 v[90:91], v[122:123], v[122:123]
	v_pk_mov_b32 v[88:89], v[122:123], v[122:123]
	v_pk_mov_b32 v[78:79], v[122:123], v[122:123]
	v_pk_mov_b32 v[76:77], v[122:123], v[122:123]
	v_pk_mov_b32 v[74:75], v[122:123], v[122:123]
	v_pk_mov_b32 v[72:73], v[122:123], v[122:123]
	v_pk_mov_b32 v[118:119], v[122:123], v[122:123]
	v_pk_mov_b32 v[116:117], v[122:123], v[122:123]
	v_pk_mov_b32 v[114:115], v[122:123], v[122:123]
	v_pk_mov_b32 v[112:113], v[122:123], v[122:123]
	v_pk_mov_b32 v[102:103], v[122:123], v[122:123]
	v_pk_mov_b32 v[100:101], v[122:123], v[122:123]
	v_pk_mov_b32 v[98:99], v[122:123], v[122:123]
	v_pk_mov_b32 v[96:97], v[122:123], v[122:123]
	v_pk_mov_b32 v[86:87], v[122:123], v[122:123]
	v_pk_mov_b32 v[84:85], v[122:123], v[122:123]
	v_pk_mov_b32 v[82:83], v[122:123], v[122:123]
	v_pk_mov_b32 v[80:81], v[122:123], v[122:123]
	v_pk_mov_b32 v[70:71], v[122:123], v[122:123]
	v_pk_mov_b32 v[68:69], v[122:123], v[122:123]
	v_pk_mov_b32 v[66:67], v[122:123], v[122:123]
	v_pk_mov_b32 v[64:65], v[122:123], v[122:123]
	v_pk_mov_b32 v[62:63], v[122:123], v[122:123]
	v_pk_mov_b32 v[60:61], v[122:123], v[122:123]
	v_pk_mov_b32 v[58:59], v[122:123], v[122:123]
	v_pk_mov_b32 v[56:57], v[122:123], v[122:123]
	v_pk_mov_b32 v[46:47], v[122:123], v[122:123]
	v_pk_mov_b32 v[44:45], v[122:123], v[122:123]
	v_pk_mov_b32 v[42:43], v[122:123], v[122:123]
	v_pk_mov_b32 v[40:41], v[122:123], v[122:123]
	v_pk_mov_b32 v[30:31], v[122:123], v[122:123]
	v_pk_mov_b32 v[28:29], v[122:123], v[122:123]
	v_pk_mov_b32 v[26:27], v[122:123], v[122:123]
	v_pk_mov_b32 v[24:25], v[122:123], v[122:123]
	v_pk_mov_b32 v[14:15], v[122:123], v[122:123]
	v_pk_mov_b32 v[12:13], v[122:123], v[122:123]
	v_pk_mov_b32 v[10:11], v[122:123], v[122:123]
	v_pk_mov_b32 v[8:9], v[122:123], v[122:123]
	v_pk_mov_b32 v[54:55], v[122:123], v[122:123]
	v_pk_mov_b32 v[52:53], v[122:123], v[122:123]
	v_pk_mov_b32 v[50:51], v[122:123], v[122:123]
	v_pk_mov_b32 v[48:49], v[122:123], v[122:123]
	v_pk_mov_b32 v[38:39], v[122:123], v[122:123]
	v_pk_mov_b32 v[36:37], v[122:123], v[122:123]
	v_pk_mov_b32 v[34:35], v[122:123], v[122:123]
	v_pk_mov_b32 v[32:33], v[122:123], v[122:123]
	v_pk_mov_b32 v[22:23], v[122:123], v[122:123]
	v_pk_mov_b32 v[20:21], v[122:123], v[122:123]
	v_pk_mov_b32 v[18:19], v[122:123], v[122:123]
	v_pk_mov_b32 v[16:17], v[122:123], v[122:123]
	v_pk_mov_b32 v[6:7], v[122:123], v[122:123]
	v_pk_mov_b32 v[4:5], v[122:123], v[122:123]
	v_pk_mov_b32 v[2:3], v[122:123], v[122:123]
	v_pk_mov_b32 v[0:1], v[122:123], v[122:123]
	s_cbranch_vccnz .LBB0_830
	s_and_b64 s[44:45], s[6:7], exec
	s_cselect_b32 s31, s37, s43
	s_cselect_b32 s35, s36, s42
	s_cselect_b32 s67, s39, s41
	s_cselect_b32 s68, s38, s40
	s_add_u32 s69, s40, 0x100
	s_addc_u32 s70, s41, 0
	s_add_u32 s40, s42, 0x80080
	s_addc_u32 s41, s43, 0
	s_mov_b32 s42, 0

;     __host__ __device__ bool next(int i, Unit& u) const { return i < cnt ? so.next(base + i, u) : false; }
;     __host__ __device__ bool next(int i, Unit& u) const { const int L = i * G + c; if (L >= 32) return false; u.g = L >> 3; u.pm = L & 7; u.pn = 0; return true; }
;   __device__ __forceinline__ bool next(int i,AttnUnit&u)const{ if(i>=4)return false; const int s=vcu&7; u.bh=vcu>>3; u.qb=(i==0)?s:(i==1)?15-s:(i==2)?16+s:31-s; return true; }
; template <class Epi, class Sched, bool ALIGN_EPI = false, bool SP2 = false>
; __device__ __forceinline__ void gemm_phase(PG8_LAS unsigned char* lds, const Gemm g, const Sched& S, const Epi& E) {
;     ...
;         const bool has_next = S.next(ui + 1, nxt);
;         const char* nA = has_next ? (const char*)(g.A + (size_t)nxt.g * g.gsA) + (size_t)nxt.pm * tstepA : cA; const char* nB = has_next ? (const char*)(g.Bt + (size_t)nxt.g * g.gsB) + (size_t)nxt.pn * tstepB : cB;
;         for (int t = 0; t < nt; t += 2) {
;             if constexpr (Epi::MIDK) { if (t == (nt >> 1)) { asm volatile("s_waitcnt vmcnt(0)" ::: "memory"); E.mid(acc, cur, wr, wc, fr, fq); asm volatile("s_waitcnt vmcnt(0)" ::: "memory"); } }
;             const bool last = (t == nt - 2);
;             const char* a1 = cA + (size_t)(t + 1) * kstep;
;             const char* a2 = last ? nA : cA + (size_t)(t + 2) * kstep; const char* b2 = last ? nB : cB + (size_t)(t + 2) * kstep;
;             const char* a3 = a2 + kstep; const char* b3 = b2 + kstep;
;     ...
; #pragma unroll
;         for (int a = 0; a < 2; ++a)
; #pragma unroll
;             for (int b = 0; b < 2; ++b)
; #pragma unroll
;                 for (int m = 0; m < 4; ++m)
; #pragma unroll
;                     for (int n = 0; n < 2; ++n) acc[a][b][m][n] = (f32x4){0.f, 0.f, 0.f, 0.f};
.LBB0_897:
	s_ashr_i32 s29, s28, 31
	s_lshl_b64 s[30:31], s[28:29], 22
	s_add_u32 s30, s45, s30
	s_addc_u32 s31, s46, s31
	s_ashr_i32 s27, s26, 31
	s_lshl_b64 s[34:35], s[26:27], 22
	s_add_u32 s34, s47, s34
	v_mov_b32_e32 v127, 0
	s_addc_u32 s35, s48, s35
	s_andn2_b64 vcc, exec, s[12:13]
	v_mov_b32_e32 v126, v127
	v_pk_mov_b32 v[124:125], v[126:127], v[126:127]
	v_pk_mov_b32 v[122:123], v[126:127], v[126:127]
	v_pk_mov_b32 v[120:121], v[126:127], v[126:127]
	v_pk_mov_b32 v[110:111], v[126:127], v[126:127]
	v_pk_mov_b32 v[108:109], v[126:127], v[126:127]
	v_pk_mov_b32 v[106:107], v[126:127], v[126:127]
	v_pk_mov_b32 v[104:105], v[126:127], v[126:127]
	v_pk_mov_b32 v[94:95], v[126:127], v[126:127]
	v_pk_mov_b32 v[92:93], v[126:127], v[126:127]
	v_pk_mov_b32 v[90:91], v[126:127], v[126:127]
	v_pk_mov_b32 v[88:89], v[126:127], v[126:127]
	v_pk_mov_b32 v[78:79], v[126:127], v[126:127]
	v_pk_mov_b32 v[76:77], v[126:127], v[126:127]
	v_pk_mov_b32 v[74:75], v[126:127], v[126:127]
	v_pk_mov_b32 v[72:73], v[126:127], v[126:127]
	v_pk_mov_b32 v[118:119], v[126:127], v[126:127]
	v_pk_mov_b32 v[116:117], v[126:127], v[126:127]
	v_pk_mov_b32 v[114:115], v[126:127], v[126:127]
	v_pk_mov_b32 v[112:113], v[126:127], v[126:127]
	v_pk_mov_b32 v[102:103], v[126:127], v[126:127]
	v_pk_mov_b32 v[100:101], v[126:127], v[126:127]
	v_pk_mov_b32 v[98:99], v[126:127], v[126:127]
	v_pk_mov_b32 v[96:97], v[126:127], v[126:127]
	v_pk_mov_b32 v[86:87], v[126:127], v[126:127]
	v_pk_mov_b32 v[84:85], v[126:127], v[126:127]
	v_pk_mov_b32 v[82:83], v[126:127], v[126:127]
	v_pk_mov_b32 v[80:81], v[126:127], v[126:127]
	v_pk_mov_b32 v[70:71], v[126:127], v[126:127]
	v_pk_mov_b32 v[68:69], v[126:127], v[126:127]
	v_pk_mov_b32 v[66:67], v[126:127], v[126:127]
	v_pk_mov_b32 v[64:65], v[126:127], v[126:127]
	v_pk_mov_b32 v[62:63], v[126:127], v[126:127]
	v_pk_mov_b32 v[60:61], v[126:127], v[126:127]
	v_pk_mov_b32 v[58:59], v[126:127], v[126:127]
	v_pk_mov_b32 v[56:57], v[126:127], v[126:127]
	v_pk_mov_b32 v[46:47], v[126:127], v[126:127]
	v_pk_mov_b32 v[44:45], v[126:127], v[126:127]
	v_pk_mov_b32 v[42:43], v[126:127], v[126:127]
	v_pk_mov_b32 v[40:41], v[126:127], v[126:127]
	v_pk_mov_b32 v[30:31], v[126:127], v[126:127]
	v_pk_mov_b32 v[28:29], v[126:127], v[126:127]
	v_pk_mov_b32 v[26:27], v[126:127], v[126:127]
	v_pk_mov_b32 v[24:25], v[126:127], v[126:127]
	v_pk_mov_b32 v[14:15], v[126:127], v[126:127]
	v_pk_mov_b32 v[12:13], v[126:127], v[126:127]
	v_pk_mov_b32 v[10:11], v[126:127], v[126:127]
	v_pk_mov_b32 v[8:9], v[126:127], v[126:127]
	v_pk_mov_b32 v[54:55], v[126:127], v[126:127]
	v_pk_mov_b32 v[52:53], v[126:127], v[126:127]
	v_pk_mov_b32 v[50:51], v[126:127], v[126:127]
	v_pk_mov_b32 v[48:49], v[126:127], v[126:127]
	v_pk_mov_b32 v[38:39], v[126:127], v[126:127]
	v_pk_mov_b32 v[36:37], v[126:127], v[126:127]
	v_pk_mov_b32 v[34:35], v[126:127], v[126:127]
	v_pk_mov_b32 v[32:33], v[126:127], v[126:127]
	v_pk_mov_b32 v[22:23], v[126:127], v[126:127]
	v_pk_mov_b32 v[20:21], v[126:127], v[126:127]
	v_pk_mov_b32 v[18:19], v[126:127], v[126:127]
	v_pk_mov_b32 v[16:17], v[126:127], v[126:127]
	v_pk_mov_b32 v[6:7], v[126:127], v[126:127]
	v_pk_mov_b32 v[4:5], v[126:127], v[126:127]
	s_waitcnt lgkmcnt(0)
	v_pk_mov_b32 v[2:3], v[126:127], v[126:127]
	v_pk_mov_b32 v[0:1], v[126:127], v[126:127]
	s_cbranch_vccnz .LBB0_900
	s_and_b64 s[42:43], s[6:7], exec
	s_cselect_b32 s27, s31, s41
	s_cselect_b32 s29, s30, s40
	s_cselect_b32 s65, s35, s39
	s_cselect_b32 s66, s34, s38
	s_add_u32 s67, s38, 0x100
	s_addc_u32 s68, s39, 0
	s_add_u32 s38, s40, 0x200080
	s_addc_u32 s39, s41, 0
	s_mov_b32 s40, 0

;     __host__ __device__ bool next(int i, Unit& u) const { return i < cnt ? so.next(base + i, u) : false; }
;     __host__ __device__ bool next(int i, Unit& u) const { const int L = i * G + c; if (L >= 32) return false; u.g = L >> 3; u.pm = L & 7; u.pn = 0; return true; }
;   __device__ __forceinline__ bool next(int i,AttnUnit&u)const{ if(i>=4)return false; const int s=vcu&7; u.bh=vcu>>3; u.qb=(i==0)?s:(i==1)?15-s:(i==2)?16+s:31-s; return true; }
; template <class Epi, class Sched, bool ALIGN_EPI = false, bool SP2 = false>
; __device__ __forceinline__ void gemm_phase(PG8_LAS unsigned char* lds, const Gemm g, const Sched& S, const Epi& E) {
;     ...
;         const bool has_next = S.next(ui + 1, nxt);
;         const char* nA = has_next ? (const char*)(g.A + (size_t)nxt.g * g.gsA) + (size_t)nxt.pm * tstepA : cA; const char* nB = has_next ? (const char*)(g.Bt + (size_t)nxt.g * g.gsB) + (size_t)nxt.pn * tstepB : cB;
;         for (int t = 0; t < nt; t += 2) {
;             if constexpr (Epi::MIDK) { if (t == (nt >> 1)) { asm volatile("s_waitcnt vmcnt(0)" ::: "memory"); E.mid(acc, cur, wr, wc, fr, fq); asm volatile("s_waitcnt vmcnt(0)" ::: "memory"); } }
;             const bool last = (t == nt - 2);
;             const char* a1 = cA + (size_t)(t + 1) * kstep;
;             const char* a2 = last ? nA : cA + (size_t)(t + 2) * kstep; const char* b2 = last ? nB : cB + (size_t)(t + 2) * kstep;
;             const char* a3 = a2 + kstep; const char* b3 = b2 + kstep;
;     ...
; #pragma unroll
;         for (int a = 0; a < 2; ++a)
; #pragma unroll
;             for (int b = 0; b < 2; ++b)
; #pragma unroll
;                 for (int m = 0; m < 4; ++m)
; #pragma unroll
;                     for (int n = 0; n < 2; ++n) acc[a][b][m][n] = (f32x4){0.f, 0.f, 0.f, 0.f};
.LBB0_986:
	s_ashr_i32 s35, s34, 31
	s_lshl_b64 s[36:37], s[34:35], 17
	s_add_u32 s36, s48, s36
	s_addc_u32 s37, s49, s37
	s_ashr_i32 s31, s30, 31
	s_lshl_b64 s[38:39], s[30:31], 17
	s_add_u32 s38, s50, s38
	v_mov_b32_e32 v127, 0
	s_addc_u32 s39, s51, s39
	s_and_b64 vcc, exec, s[6:7]
	v_mov_b32_e32 v126, v127
	v_pk_mov_b32 v[124:125], v[126:127], v[126:127]
	v_pk_mov_b32 v[122:123], v[126:127], v[126:127]
	v_pk_mov_b32 v[120:121], v[126:127], v[126:127]
	v_pk_mov_b32 v[110:111], v[126:127], v[126:127]
	v_pk_mov_b32 v[108:109], v[126:127], v[126:127]
	v_pk_mov_b32 v[106:107], v[126:127], v[126:127]
	v_pk_mov_b32 v[104:105], v[126:127], v[126:127]
	v_pk_mov_b32 v[94:95], v[126:127], v[126:127]
	v_pk_mov_b32 v[92:93], v[126:127], v[126:127]
	v_pk_mov_b32 v[90:91], v[126:127], v[126:127]
	v_pk_mov_b32 v[88:89], v[126:127], v[126:127]
	v_pk_mov_b32 v[78:79], v[126:127], v[126:127]
	v_pk_mov_b32 v[76:77], v[126:127], v[126:127]
	v_pk_mov_b32 v[74:75], v[126:127], v[126:127]
	v_pk_mov_b32 v[72:73], v[126:127], v[126:127]
	v_pk_mov_b32 v[118:119], v[126:127], v[126:127]
	v_pk_mov_b32 v[116:117], v[126:127], v[126:127]
	v_pk_mov_b32 v[114:115], v[126:127], v[126:127]
	v_pk_mov_b32 v[112:113], v[126:127], v[126:127]
	v_pk_mov_b32 v[102:103], v[126:127], v[126:127]
	v_pk_mov_b32 v[100:101], v[126:127], v[126:127]
	v_pk_mov_b32 v[98:99], v[126:127], v[126:127]
	v_pk_mov_b32 v[96:97], v[126:127], v[126:127]
	v_pk_mov_b32 v[86:87], v[126:127], v[126:127]
	v_pk_mov_b32 v[84:85], v[126:127], v[126:127]
	v_pk_mov_b32 v[82:83], v[126:127], v[126:127]
	v_pk_mov_b32 v[80:81], v[126:127], v[126:127]
	v_pk_mov_b32 v[70:71], v[126:127], v[126:127]
	v_pk_mov_b32 v[68:69], v[126:127], v[126:127]
	v_pk_mov_b32 v[66:67], v[126:127], v[126:127]
	v_pk_mov_b32 v[64:65], v[126:127], v[126:127]
	v_pk_mov_b32 v[62:63], v[126:127], v[126:127]
	v_pk_mov_b32 v[60:61], v[126:127], v[126:127]
	v_pk_mov_b32 v[58:59], v[126:127], v[126:127]
	v_pk_mov_b32 v[56:57], v[126:127], v[126:127]
	v_pk_mov_b32 v[46:47], v[126:127], v[126:127]
	v_pk_mov_b32 v[44:45], v[126:127], v[126:127]
	v_pk_mov_b32 v[42:43], v[126:127], v[126:127]
	v_pk_mov_b32 v[40:41], v[126:127], v[126:127]
	v_pk_mov_b32 v[30:31], v[126:127], v[126:127]
	v_pk_mov_b32 v[28:29], v[126:127], v[126:127]
	v_pk_mov_b32 v[26:27], v[126:127], v[126:127]
	v_pk_mov_b32 v[24:25], v[126:127], v[126:127]
	v_pk_mov_b32 v[14:15], v[126:127], v[126:127]
	v_pk_mov_b32 v[12:13], v[126:127], v[126:127]
	v_pk_mov_b32 v[10:11], v[126:127], v[126:127]
	v_pk_mov_b32 v[8:9], v[126:127], v[126:127]
	v_pk_mov_b32 v[54:55], v[126:127], v[126:127]
	v_pk_mov_b32 v[52:53], v[126:127], v[126:127]
	v_pk_mov_b32 v[50:51], v[126:127], v[126:127]
	v_pk_mov_b32 v[48:49], v[126:127], v[126:127]
	v_pk_mov_b32 v[38:39], v[126:127], v[126:127]
	v_pk_mov_b32 v[36:37], v[126:127], v[126:127]
	v_pk_mov_b32 v[34:35], v[126:127], v[126:127]
	v_pk_mov_b32 v[32:33], v[126:127], v[126:127]
	v_pk_mov_b32 v[22:23], v[126:127], v[126:127]
	v_pk_mov_b32 v[20:21], v[126:127], v[126:127]
	v_pk_mov_b32 v[18:19], v[126:127], v[126:127]
	v_pk_mov_b32 v[16:17], v[126:127], v[126:127]
	v_pk_mov_b32 v[6:7], v[126:127], v[126:127]
	v_pk_mov_b32 v[4:5], v[126:127], v[126:127]
	v_pk_mov_b32 v[2:3], v[126:127], v[126:127]
	v_pk_mov_b32 v[0:1], v[126:127], v[126:127]
	s_cbranch_vccnz .LBB0_989
	s_and_b64 s[44:45], s[8:9], exec
	s_cselect_b32 s31, s37, s43
	s_cselect_b32 s35, s36, s42
	s_cselect_b32 s67, s39, s41
	s_cselect_b32 s68, s38, s40
	s_add_u32 s69, s40, 0x100
	s_addc_u32 s70, s41, 0
	s_add_u32 s40, s42, 0x10080
	s_addc_u32 s41, s43, 0
	s_mov_b32 s42, 0
